# ffn_fixup items remapped to the owner group; group barriers also at fixup->down and RWKV RW1->RW2 (6 seam kinds now group-local)
# speedup vs baseline: 1.0118x; 1.0005x over previous
.LBB0_851:
	v_readlane_b32 s0, v253, 37
	v_readlane_b32 s16, v250, 0
	s_or_b32 s0, s0, 4
	v_readlane_b32 s19, v250, 3
	s_cmp_ge_i32 s0, s19
	v_readlane_b32 s17, v250, 1
	v_readlane_b32 s18, v250, 2
	s_cbranch_scc1 .LBB0_907
	s_waitcnt vmcnt(0)
	v_readlane_b32 s2, v253, 40
	v_readlane_b32 s3, v253, 41
	s_and_b64 vcc, exec, s[2:3]
	s_waitcnt vmcnt(0) lgkmcnt(0)
	s_barrier
	s_cbranch_vccnz .LBB0_906
	s_cmp_lg_u32 s101, 0
	s_cbranch_scc1 .Lmy_gchk_4
	s_mov_b32 s101, 2
	s_cmp_lg_u32 s94, 0x100
	s_cbranch_scc1 .Lmy_gchk_4
	v_readlane_b32 s8, v250, 0
	v_readlane_b32 s9, v250, 1
	s_mov_b32 s2, -1
	v_mbcnt_lo_u32_b32 v0, s2, 0
	v_mbcnt_hi_u32_b32 v0, s2, v0
	v_lshlrev_b32_e32 v0, 2, v0
	s_add_u32 s8, s8, 0x60000
	s_addc_u32 s9, s9, 0
	global_load_dword v1, v0, s[8:9] sc0 sc1
	global_load_dword v2, v0, s[8:9] offset:256 sc0 sc1
	global_load_dword v3, v0, s[8:9] offset:512 sc0 sc1
	global_load_dword v4, v0, s[8:9] offset:768 sc0 sc1
	s_waitcnt vmcnt(0)
	v_cmp_ne_u32_e32 vcc, 0, v1
	v_cmp_eq_u32_e64 s[2:3], v1, v2
	v_cmp_eq_u32_e64 s[12:13], v1, v3
	s_and_b64 s[2:3], s[2:3], vcc
	v_cmp_eq_u32_e64 s[8:9], v1, v4
	s_and_b64 s[2:3], s[2:3], s[12:13]
	s_and_b64 s[2:3], s[2:3], s[8:9]
	s_cmp_eq_u64 s[2:3], -1
	s_cbranch_scc0 .Lmy_gchk_4
	s_mov_b32 s101, 1
.Lmy_gchk_4:
	s_mov_b32 s2, -1
	s_nop 0
	v_mbcnt_lo_u32_b32 v0, s2, 0
	v_mbcnt_hi_u32_b32 v0, s2, v0
	s_nop 0
	v_cmp_eq_u32_e32 vcc, 0, v0
	s_and_saveexec_b64 s[16:17], vcc
	s_cbranch_execz .LBB0_905
	s_cmp_lg_u32 s101, 1
	s_cbranch_scc1 .Lmy_gfull_4
	v_readlane_b32 s2, v253, 37
	v_readlane_b32 s3, v250, 7
	v_readlane_b32 s8, v250, 0
	v_readlane_b32 s9, v250, 1
	s_lshl_b32 s2, s2, 11
	s_add_i32 s2, s2, 0x4000
	s_and_b32 s3, s3, 63
	s_lshl_b32 s3, s3, 6
	s_add_i32 s2, s2, s3
	s_add_u32 s8, s8, 0x70000
	s_addc_u32 s9, s9, 0
	v_mov_b32_e32 v0, s2
	v_mov_b32_e32 v1, 1
	s_waitcnt vmcnt(0) lgkmcnt(0)
	global_atomic_add v0, v1, s[8:9]
	s_mov_b32 s2, 0

.Lmy_gchk_0:
	s_mov_b32 s2, -1
	s_nop 0
	v_mbcnt_lo_u32_b32 v0, s2, 0
	v_mbcnt_hi_u32_b32 v0, s2, v0
	s_nop 0
	v_cmp_eq_u32_e32 vcc, 0, v0
	s_and_saveexec_b64 s[16:17], vcc
	s_cbranch_execz .LBB0_1954
	s_cmp_lg_u32 s101, 1
	s_cbranch_scc1 .Lmy_gfull_0
	v_readlane_b32 s2, v253, 37
	v_readlane_b32 s3, v250, 7
	v_readlane_b32 s8, v250, 0
	v_readlane_b32 s9, v250, 1
	s_lshl_b32 s2, s2, 11
	s_add_i32 s2, s2, 0x0
	s_and_b32 s3, s3, 63
	s_lshl_b32 s3, s3, 6
	s_add_i32 s2, s2, s3
	s_add_u32 s8, s8, 0x70000
	s_addc_u32 s9, s9, 0
	v_mov_b32_e32 v0, s2
	v_mov_b32_e32 v1, 1
	s_waitcnt vmcnt(0) lgkmcnt(0)
	global_atomic_add v0, v1, s[8:9]
	s_mov_b32 s2, 0

.Lmy_gchk_3:
	s_mov_b32 s2, -1
	s_nop 0
	v_mbcnt_lo_u32_b32 v0, s2, 0
	v_mbcnt_hi_u32_b32 v0, s2, v0
	s_nop 0
	v_cmp_eq_u32_e32 vcc, 0, v0
	s_and_saveexec_b64 s[16:17], vcc
	s_cbranch_execz .LBB0_2032
	s_cmp_lg_u32 s101, 1
	s_cbranch_scc1 .Lmy_gfull_3
	v_readlane_b32 s2, v253, 37
	v_readlane_b32 s3, v250, 7
	v_readlane_b32 s8, v250, 0
	v_readlane_b32 s9, v250, 1
	s_cmp_eq_u32 s2, 32
	s_cbranch_scc1 .Lmy_gfull_3
	s_lshl_b32 s2, s2, 11
	s_add_i32 s2, s2, 0x3000
	s_and_b32 s3, s3, 63
	s_lshl_b32 s3, s3, 6
	s_add_i32 s2, s2, s3
	s_add_u32 s8, s8, 0x70000
	s_addc_u32 s9, s9, 0
	v_mov_b32_e32 v0, s2
	v_mov_b32_e32 v1, 1
	s_waitcnt vmcnt(0) lgkmcnt(0)
	global_atomic_add v0, v1, s[8:9]
	s_mov_b32 s2, 0

.LBB0_2158:
	s_andn2_b64 vcc, exec, s[8:9]
	s_cbranch_vccnz .LBB0_2220
	s_mov_b32 s0, s80
	s_mov_b32 s2, -1
	s_lshl_b32 s0, s0, 6
	v_mbcnt_lo_u32_b32 v0, s2, 0
	v_mbcnt_hi_u32_b32 v0, s2, v0
	v_readlane_b32 s2, v250, 6
	s_mov_b32 s99, 0x2b000
	s_mov_b32 s98, s78
	s_cmp_lg_u32 s94, 0x100
	s_cbranch_scc1 .Lmy_fxmap
	v_readlane_b32 s99, v250, 7
	s_and_b32 s98, s99, 7
	s_lshl_b32 s98, s98, 3
	s_bfe_u32 s2, s99, 0x30003
	s_or_b32 s98, s98, s2
	s_lshl_b32 s98, s98, 2
	s_lshr_b32 s99, s99, 6
	s_or_b32 s99, s99, s98
	s_mul_i32 s2, s99, 0x2b0
	s_add_i32 s99, s2, 0x2b0
	s_movk_i32 s98, 0x200
.Lmy_fxmap:
	s_add_i32 s0, s0, s2
	s_mov_b64 s[20:21], s[96:97]
	v_add_u32_e32 v4, s0, v0
	s_mov_b32 s0, s99
	s_mov_b64 s[16:17], s[96:97]
	s_mov_b64 s[12:13], s[96:97]
	s_mov_b64 s[18:19], s[96:97]
	v_cmp_gt_i32_e32 vcc, s0, v4
	s_and_saveexec_b64 s[8:9], vcc
	s_cbranch_execz .LBB0_2164
	s_load_dwordx2 s[2:3], s[20:21], 0x110
	s_nop 0
	s_load_dwordx2 s[16:17], s[16:17], 0xe0
	s_mul_i32 s7, s48, 0x20400
	s_load_dwordx2 s[20:21], s[12:13], 0xe8
	s_mul_hi_u32 s0, s48, 0x20400
	s_waitcnt lgkmcnt(0)
	s_add_u32 s12, s2, 0x22b00000
	s_addc_u32 s13, s3, 0
	s_load_dwordx2 s[2:3], s[18:19], 0x110
	s_add_u32 s16, s16, s7
	s_addc_u32 s17, s17, s0
	s_mul_i32 s7, s48, 0xac00
	s_mul_hi_u32 s0, s48, 0xac00
	s_add_u32 s18, s20, s7
	s_addc_u32 s19, s21, s0
	s_waitcnt lgkmcnt(0)
	s_add_u32 s20, s2, 0x38300000
	s_addc_u32 s21, s3, 0
	s_add_u32 s22, s16, 0x15800
	s_addc_u32 s23, s17, 0
	s_add_u32 s26, s16, 0xac00
	s_addc_u32 s27, s17, 0
	v_lshlrev_b32_e32 v5, 2, v4
	s_lshl_b32 s0, s98, 2
	v_lshlrev_b32_e32 v6, 3, v4
	s_lshl_b32 s2, s98, 3
	s_mov_b64 s[34:35], 0
	s_branch .LBB0_2162
.LBB0_2161:
	s_or_b64 exec, exec, s[28:29]
	v_add_u32_e32 v4, s98, v4
	s_add_i32 s3, s99, -1
	v_cmp_lt_i32_e32 vcc, s3, v4
	v_add_u32_e32 v5, s0, v5
	s_or_b64 s[34:35], vcc, s[34:35]
	v_add_u32_e32 v6, s2, v6
	s_andn2_b64 exec, exec, s[34:35]
	s_cbranch_execz .LBB0_2164

.LBB0_2164:
	s_or_b64 exec, exec, s[8:9]
	v_readlane_b32 s0, v253, 37
	v_readlane_b32 s16, v250, 0
	s_or_b32 s0, s0, 13
	v_readlane_b32 s19, v250, 3
	s_cmp_ge_i32 s0, s19
	v_readlane_b32 s17, v250, 1
	v_readlane_b32 s18, v250, 2
	s_cbranch_scc1 .LBB0_2220
	s_waitcnt vmcnt(0)
	v_readlane_b32 s2, v253, 40
	v_readlane_b32 s3, v253, 41
	s_and_b64 vcc, exec, s[2:3]
	s_waitcnt vmcnt(0) lgkmcnt(0)
	s_barrier
	s_cbranch_vccnz .LBB0_2219
	s_cmp_lg_u32 s101, 0
	s_cbranch_scc1 .Lmy_gchk_5
	s_mov_b32 s101, 2
	s_cmp_lg_u32 s94, 0x100
	s_cbranch_scc1 .Lmy_gchk_5
	v_readlane_b32 s8, v250, 0
	v_readlane_b32 s9, v250, 1
	s_mov_b32 s2, -1
	v_mbcnt_lo_u32_b32 v0, s2, 0
	v_mbcnt_hi_u32_b32 v0, s2, v0
	v_lshlrev_b32_e32 v0, 2, v0
	s_add_u32 s8, s8, 0x60000
	s_addc_u32 s9, s9, 0
	global_load_dword v1, v0, s[8:9] sc0 sc1
	global_load_dword v2, v0, s[8:9] offset:256 sc0 sc1
	global_load_dword v3, v0, s[8:9] offset:512 sc0 sc1
	global_load_dword v4, v0, s[8:9] offset:768 sc0 sc1
	s_waitcnt vmcnt(0)
	v_cmp_ne_u32_e32 vcc, 0, v1
	v_cmp_eq_u32_e64 s[2:3], v1, v2
	v_cmp_eq_u32_e64 s[12:13], v1, v3
	s_and_b64 s[2:3], s[2:3], vcc
	v_cmp_eq_u32_e64 s[8:9], v1, v4
	s_and_b64 s[2:3], s[2:3], s[12:13]
	s_and_b64 s[2:3], s[2:3], s[8:9]
	s_cmp_eq_u64 s[2:3], -1
	s_cbranch_scc0 .Lmy_gchk_5
	s_mov_b32 s101, 1
.Lmy_gchk_5:
	s_mov_b32 s2, -1
	s_nop 0
	v_mbcnt_lo_u32_b32 v0, s2, 0
	v_mbcnt_hi_u32_b32 v0, s2, v0
	s_nop 0
	v_cmp_eq_u32_e32 vcc, 0, v0
	s_and_saveexec_b64 s[16:17], vcc
	s_cbranch_execz .LBB0_2218
	s_cmp_lg_u32 s101, 1
	s_cbranch_scc1 .Lmy_gfull_5
	v_readlane_b32 s2, v253, 37
	v_readlane_b32 s3, v250, 7
	v_readlane_b32 s8, v250, 0
	v_readlane_b32 s9, v250, 1
	s_lshl_b32 s2, s2, 11
	s_add_i32 s2, s2, 0x5000
	s_and_b32 s3, s3, 63
	s_lshl_b32 s3, s3, 6
	s_add_i32 s2, s2, s3
	s_add_u32 s8, s8, 0x70000
	s_addc_u32 s9, s9, 0
	v_mov_b32_e32 v0, s2
	v_mov_b32_e32 v1, 1
	s_waitcnt vmcnt(0) lgkmcnt(0)
	global_atomic_add v0, v1, s[8:9]
	s_mov_b32 s2, 0

.Lmy_gchk_1:
	s_mov_b32 s2, -1
	s_nop 0
	v_mbcnt_lo_u32_b32 v0, s2, 0
	v_mbcnt_hi_u32_b32 v0, s2, v0
	s_nop 0
	v_cmp_eq_u32_e32 vcc, 0, v0
	s_and_saveexec_b64 s[16:17], vcc
	s_cbranch_execz .LBB0_2303
	s_cmp_lg_u32 s101, 1
	s_cbranch_scc1 .Lmy_gfull_1
	v_readlane_b32 s2, v253, 37
	v_readlane_b32 s3, v250, 7
	v_readlane_b32 s8, v250, 0
	v_readlane_b32 s9, v250, 1
	s_lshl_b32 s2, s2, 11
	s_add_i32 s2, s2, 0x1000
	s_and_b32 s3, s3, 63
	s_lshl_b32 s3, s3, 6
	s_add_i32 s2, s2, s3
	s_add_u32 s8, s8, 0x70000
	s_addc_u32 s9, s9, 0
	v_mov_b32_e32 v0, s2
	v_mov_b32_e32 v1, 1
	s_waitcnt vmcnt(0) lgkmcnt(0)
	global_atomic_add v0, v1, s[8:9]
	s_mov_b32 s2, 0

.Lmy_gchk_2:
	s_mov_b32 s2, -1
	s_nop 0
	v_mbcnt_lo_u32_b32 v0, s2, 0
	v_mbcnt_hi_u32_b32 v0, s2, v0
	s_nop 0
	v_cmp_eq_u32_e32 vcc, 0, v0
	s_and_saveexec_b64 s[16:17], vcc
	s_cbranch_execz .LBB0_2381
	s_cmp_lg_u32 s101, 1
	s_cbranch_scc1 .Lmy_gfull_2
	v_readlane_b32 s2, v253, 37
	v_readlane_b32 s3, v250, 7
	v_readlane_b32 s8, v250, 0
	v_readlane_b32 s9, v250, 1
	s_lshl_b32 s2, s2, 11
	s_add_i32 s2, s2, 0x2000
	s_and_b32 s3, s3, 63
	s_lshl_b32 s3, s3, 6
	s_add_i32 s2, s2, s3
	s_add_u32 s8, s8, 0x70000
	s_addc_u32 s9, s9, 0
	v_mov_b32_e32 v0, s2
	v_mov_b32_e32 v1, 1
	s_waitcnt vmcnt(0) lgkmcnt(0)
	global_atomic_add v0, v1, s[8:9]
	s_mov_b32 s2, 0
